# HGRN prep waves: LDS-DMA issue interleaved with the scan VALU, zq fetched one chunk ahead during the scan
# baseline (speedup 1.0000x reference)
.Lh2_prep:
	v_and_b32_e32 v244, 63, v200
	v_lshrrev_b32_e32 v245, 2, v244
	v_lshrrev_b32_e32 v243, 4, v244
	s_lshl_b32 s1, s8, 12
	s_add_u32 s13, s1, 0xfff
	s_cmp_eq_u32 s12, 0
	s_cselect_b64 s[18:19], -1, 0
	v_mov_b32_e32 v242, 0x1c00
	v_and_b32_e32 v241, 3, v244
	v_and_b32_e32 v240, 3, v243
	v_xor_b32_e32 v241, v241, v240
	v_lshlrev_b32_e32 v241, 4, v241
	v_add_u32_e32 v240, 0, v245
	v_add_u32_e32 v239, s1, v240
	v_sub_u32_e32 v240, s13, v240
	v_cndmask_b32_e64 v239, v240, v239, s[18:19]
	v_mul_lo_u32 v239, v239, v242
	v_add_u32_e32 v228, v239, v241
	v_add_u32_e32 v240, 16, v245
	v_add_u32_e32 v239, s1, v240
	v_sub_u32_e32 v240, s13, v240
	v_cndmask_b32_e64 v239, v240, v239, s[18:19]
	v_mul_lo_u32 v239, v239, v242
	v_add_u32_e32 v230, v239, v241
	v_add_u32_e32 v240, 32, v245
	v_add_u32_e32 v239, s1, v240
	v_sub_u32_e32 v240, s13, v240
	v_cndmask_b32_e64 v239, v240, v239, s[18:19]
	v_mul_lo_u32 v239, v239, v242
	v_add_u32_e32 v231, v239, v241
	v_add_u32_e32 v240, 48, v245
	v_add_u32_e32 v239, s1, v240
	v_sub_u32_e32 v240, s13, v240
	v_cndmask_b32_e64 v239, v240, v239, s[18:19]
	v_mul_lo_u32 v239, v239, v242
	v_add_u32_e32 v232, v239, v241
	s_lshl_b32 s17, s0, 4
	v_add_u32_e32 v240, 0, v243
	v_add_u32_e32 v240, s17, v240
	v_add_u32_e32 v239, s1, v240
	v_sub_u32_e32 v240, s13, v240
	v_cndmask_b32_e64 v239, v240, v239, s[18:19]
	v_mul_lo_u32 v239, v239, v242
	v_lshl_or_b32 v240, v243, 2, 0
	v_and_b32_e32 v238, 15, v244
	v_xor_b32_e32 v240, v240, v238
	v_lshl_add_u32 v252, v240, 4, v239
	v_add_u32_e32 v240, 4, v243
	v_add_u32_e32 v240, s17, v240
	v_add_u32_e32 v239, s1, v240
	v_sub_u32_e32 v240, s13, v240
	v_cndmask_b32_e64 v239, v240, v239, s[18:19]
	v_mul_lo_u32 v239, v239, v242
	v_lshl_or_b32 v240, v243, 2, 1
	v_and_b32_e32 v238, 15, v244
	v_xor_b32_e32 v240, v240, v238
	v_lshl_add_u32 v253, v240, 4, v239
	v_add_u32_e32 v240, 8, v243
	v_add_u32_e32 v240, s17, v240
	v_add_u32_e32 v239, s1, v240
	v_sub_u32_e32 v240, s13, v240
	v_cndmask_b32_e64 v239, v240, v239, s[18:19]
	v_mul_lo_u32 v239, v239, v242
	v_lshl_or_b32 v240, v243, 2, 2
	v_and_b32_e32 v238, 15, v244
	v_xor_b32_e32 v240, v240, v238
	v_lshl_add_u32 v254, v240, 4, v239
	v_add_u32_e32 v240, 12, v243
	v_add_u32_e32 v240, s17, v240
	v_add_u32_e32 v239, s1, v240
	v_sub_u32_e32 v240, s13, v240
	v_cndmask_b32_e64 v239, v240, v239, s[18:19]
	v_mul_lo_u32 v239, v239, v242
	v_lshl_or_b32 v240, v243, 2, 3
	v_and_b32_e32 v238, 15, v244
	v_xor_b32_e32 v240, v240, v238
	v_lshl_add_u32 v255, v240, 4, v239
	s_mov_b32 s33, 0x70000
	s_sub_u32 s13, 0, s33
	s_cmp_eq_u32 s12, 0
	s_cselect_b32 s33, s33, s13
	s_lshl_b32 s13, s9, 8
	s_add_u32 s34, s92, s13
	s_addc_u32 s35, s93, 0
	s_lshl_b32 s1, s0, 6
	s_add_u32 s30, s34, s1
	s_addc_u32 s31, s35, 0
	s_add_u32 s34, s34, 0xc00
	s_addc_u32 s35, s35, 0
	s_movk_i32 s1, 0x800
	s_cmp_eq_u32 s12, 0
	s_cselect_b32 s1, 0x400, s1
	s_add_u32 s14, s30, s1
	s_addc_u32 s15, s31, 0
	v_and_b32_e32 v241, 3, v244
	v_xor_b32_e32 v241, s0, v241
	v_lshlrev_b32_e32 v241, 6, v241
	v_lshl_add_u32 v241, v244, 8, v241
	v_bfe_u32 v240, v244, 2, 2
	v_xor_b32_e32 v239, 0, v240
	v_lshl_add_u32 v222, v239, 4, v241
	v_xor_b32_e32 v239, 1, v240
	v_lshl_add_u32 v223, v239, 4, v241
	v_xor_b32_e32 v239, 2, v240
	v_lshl_add_u32 v224, v239, 4, v241
	v_xor_b32_e32 v239, 3, v240
	v_lshl_add_u32 v225, v239, 4, v241
	v_mov_b32_e32 v239, 0x110
	v_mul_lo_u32 v241, v244, v239
	s_lshl_b32 s1, s0, 6
	v_add_u32_e32 v241, s1, v241
	v_add_u32_e32 v226, 0x10400, v241
	v_add_u32_e32 v227, 0x14800, v241
	s_lshl_b32 s1, s0, 7
	v_mov_b32_e32 v247, s1
	s_lshl_b32 s71, s0, 13
	s_add_u32 s71, s71, 0x1b400
	s_lshl_b32 s72, s0, 12
	v_lshlrev_b32_e32 v241, 6, v244
	v_add_u32_e32 v241, s71, v241
	v_xor_b32_e32 v239, 0, v240
	v_lshl_add_u32 v248, v239, 4, v241
	v_xor_b32_e32 v239, 1, v240
	v_lshl_add_u32 v249, v239, 4, v241
	v_xor_b32_e32 v239, 2, v240
	v_lshl_add_u32 v250, v239, 4, v241
	v_xor_b32_e32 v239, 3, v240
	v_lshl_add_u32 v251, v239, 4, v241
	s_add_u32 m0, s71, 0
	s_nop 0
	global_load_lds_dwordx4 v228, s[14:15]
	s_add_u32 m0, s71, 4096
	s_nop 0
	global_load_lds_dwordx4 v228, s[30:31]
	s_add_u32 m0, s71, 1024
	s_nop 0
	global_load_lds_dwordx4 v230, s[14:15]
	s_add_u32 m0, s71, 5120
	s_nop 0
	global_load_lds_dwordx4 v230, s[30:31]
	s_add_u32 m0, s71, 2048
	s_nop 0
	global_load_lds_dwordx4 v231, s[14:15]
	s_add_u32 m0, s71, 6144
	s_nop 0
	global_load_lds_dwordx4 v231, s[30:31]
	s_add_u32 m0, s71, 3072
	s_nop 0
	global_load_lds_dwordx4 v232, s[14:15]
	s_add_u32 m0, s71, 7168
	s_nop 0
	global_load_lds_dwordx4 v232, s[30:31]
	v_add_u32_e32 v228, s33, v228
	v_add_u32_e32 v230, s33, v230
	v_add_u32_e32 v231, s33, v231
	v_add_u32_e32 v232, s33, v232
	s_mov_b32 s70, 0
.Lh2_prep_loop:
	s_waitcnt vmcnt(0)
	ds_read_b128 v[234:237], v248
	ds_read_b128 v[238:241], v249
	ds_read_b128 v[242:245], v250
	ds_read_b128 v[168:171], v251
	ds_read_b128 v[0:3], v248 offset:4096
	ds_read_b128 v[4:7], v249 offset:4096
	ds_read_b128 v[8:11], v250 offset:4096
	ds_read_b128 v[12:15], v251 offset:4096
	s_cmp_eq_u32 s70, 31
	s_cselect_b32 s76, 0, s33
	s_waitcnt lgkmcnt(4)
	s_add_u32 m0, s72, 33792
	s_nop 0
	global_load_lds_dwordx4 v252, s[34:35]
	v_lshlrev_b32_e32 v96, 16, v234
	v_and_b32_e32 v97, 0xffff0000, v234
	v_lshlrev_b32_e32 v98, 16, v235
	v_and_b32_e32 v99, 0xffff0000, v235
	v_lshlrev_b32_e32 v100, 16, v236
	v_and_b32_e32 v101, 0xffff0000, v236
	v_lshlrev_b32_e32 v102, 16, v237
	v_and_b32_e32 v103, 0xffff0000, v237
	v_lshlrev_b32_e32 v104, 16, v238
	v_and_b32_e32 v105, 0xffff0000, v238
	v_lshlrev_b32_e32 v106, 16, v239
	v_and_b32_e32 v107, 0xffff0000, v239
	v_lshlrev_b32_e32 v108, 16, v240
	v_and_b32_e32 v109, 0xffff0000, v240
	v_lshlrev_b32_e32 v110, 16, v241
	v_and_b32_e32 v111, 0xffff0000, v241
	v_lshlrev_b32_e32 v112, 16, v242
	v_and_b32_e32 v113, 0xffff0000, v242
	v_lshlrev_b32_e32 v114, 16, v243
	v_and_b32_e32 v115, 0xffff0000, v243
	v_lshlrev_b32_e32 v116, 16, v244
	s_add_u32 m0, s72, 34816
	s_nop 0
	global_load_lds_dwordx4 v253, s[34:35]
	v_and_b32_e32 v117, 0xffff0000, v244
	v_lshlrev_b32_e32 v118, 16, v245
	v_and_b32_e32 v119, 0xffff0000, v245
	v_lshlrev_b32_e32 v120, 16, v168
	v_and_b32_e32 v121, 0xffff0000, v168
	v_lshlrev_b32_e32 v122, 16, v169
	v_and_b32_e32 v123, 0xffff0000, v169
	v_lshlrev_b32_e32 v124, 16, v170
	v_and_b32_e32 v125, 0xffff0000, v170
	v_lshlrev_b32_e32 v126, 16, v171
	v_and_b32_e32 v127, 0xffff0000, v171
	s_waitcnt lgkmcnt(0)
	v_sub_f32_e32 v128, 1.0, v96
	v_sub_f32_e32 v129, 1.0, v97
	v_sub_f32_e32 v130, 1.0, v98
	v_sub_f32_e32 v131, 1.0, v99
	v_sub_f32_e32 v132, 1.0, v100
	v_sub_f32_e32 v133, 1.0, v101
	v_sub_f32_e32 v134, 1.0, v102
	v_sub_f32_e32 v135, 1.0, v103
	v_sub_f32_e32 v136, 1.0, v104
	v_sub_f32_e32 v137, 1.0, v105
	s_add_u32 m0, s72, 35840
	s_nop 0
	global_load_lds_dwordx4 v254, s[34:35]
	v_sub_f32_e32 v138, 1.0, v106
	v_sub_f32_e32 v139, 1.0, v107
	v_sub_f32_e32 v140, 1.0, v108
	v_sub_f32_e32 v141, 1.0, v109
	v_sub_f32_e32 v142, 1.0, v110
	v_sub_f32_e32 v143, 1.0, v111
	v_sub_f32_e32 v144, 1.0, v112
	v_sub_f32_e32 v145, 1.0, v113
	v_sub_f32_e32 v146, 1.0, v114
	v_sub_f32_e32 v147, 1.0, v115
	v_sub_f32_e32 v148, 1.0, v116
	v_sub_f32_e32 v149, 1.0, v117
	v_sub_f32_e32 v150, 1.0, v118
	v_sub_f32_e32 v151, 1.0, v119
	v_sub_f32_e32 v152, 1.0, v120
	v_sub_f32_e32 v153, 1.0, v121
	v_sub_f32_e32 v154, 1.0, v122
	v_sub_f32_e32 v155, 1.0, v123
	v_sub_f32_e32 v156, 1.0, v124
	v_sub_f32_e32 v157, 1.0, v125
	v_sub_f32_e32 v158, 1.0, v126
	s_add_u32 m0, s72, 36864
	s_nop 0
	global_load_lds_dwordx4 v255, s[34:35]
	v_add_u32_e32 v252, s33, v252
	v_add_u32_e32 v253, s33, v253
	v_add_u32_e32 v254, s33, v254
	v_add_u32_e32 v255, s33, v255
	v_sub_f32_e32 v159, 1.0, v127
	v_mul_f32_dpp v128, v128, v128 row_shr:1 row_mask:0xf bank_mask:0xf
	v_mul_f32_dpp v129, v129, v129 row_shr:1 row_mask:0xf bank_mask:0xf
	v_mul_f32_dpp v130, v130, v130 row_shr:1 row_mask:0xf bank_mask:0xf
	v_mul_f32_dpp v131, v131, v131 row_shr:1 row_mask:0xf bank_mask:0xf
	v_mul_f32_dpp v132, v132, v132 row_shr:1 row_mask:0xf bank_mask:0xf
	v_mul_f32_dpp v133, v133, v133 row_shr:1 row_mask:0xf bank_mask:0xf
	v_mul_f32_dpp v134, v134, v134 row_shr:1 row_mask:0xf bank_mask:0xf
	v_mul_f32_dpp v135, v135, v135 row_shr:1 row_mask:0xf bank_mask:0xf
	v_mul_f32_dpp v136, v136, v136 row_shr:1 row_mask:0xf bank_mask:0xf
	v_mul_f32_dpp v137, v137, v137 row_shr:1 row_mask:0xf bank_mask:0xf
	v_mul_f32_dpp v138, v138, v138 row_shr:1 row_mask:0xf bank_mask:0xf
	v_mul_f32_dpp v139, v139, v139 row_shr:1 row_mask:0xf bank_mask:0xf
	v_mul_f32_dpp v140, v140, v140 row_shr:1 row_mask:0xf bank_mask:0xf
	v_mul_f32_dpp v141, v141, v141 row_shr:1 row_mask:0xf bank_mask:0xf
	v_mul_f32_dpp v142, v142, v142 row_shr:1 row_mask:0xf bank_mask:0xf
	v_mul_f32_dpp v143, v143, v143 row_shr:1 row_mask:0xf bank_mask:0xf
	v_mul_f32_dpp v144, v144, v144 row_shr:1 row_mask:0xf bank_mask:0xf
	v_mul_f32_dpp v145, v145, v145 row_shr:1 row_mask:0xf bank_mask:0xf
	v_mul_f32_dpp v146, v146, v146 row_shr:1 row_mask:0xf bank_mask:0xf
	v_mul_f32_dpp v147, v147, v147 row_shr:1 row_mask:0xf bank_mask:0xf
	s_add_u32 m0, s71, 0
	s_nop 0
	global_load_lds_dwordx4 v228, s[14:15]
	v_mul_f32_dpp v148, v148, v148 row_shr:1 row_mask:0xf bank_mask:0xf
	v_mul_f32_dpp v149, v149, v149 row_shr:1 row_mask:0xf bank_mask:0xf
	v_mul_f32_dpp v150, v150, v150 row_shr:1 row_mask:0xf bank_mask:0xf
	v_mul_f32_dpp v151, v151, v151 row_shr:1 row_mask:0xf bank_mask:0xf
	v_mul_f32_dpp v152, v152, v152 row_shr:1 row_mask:0xf bank_mask:0xf
	v_mul_f32_dpp v153, v153, v153 row_shr:1 row_mask:0xf bank_mask:0xf
	v_mul_f32_dpp v154, v154, v154 row_shr:1 row_mask:0xf bank_mask:0xf
	v_mul_f32_dpp v155, v155, v155 row_shr:1 row_mask:0xf bank_mask:0xf
	v_mul_f32_dpp v156, v156, v156 row_shr:1 row_mask:0xf bank_mask:0xf
	v_mul_f32_dpp v157, v157, v157 row_shr:1 row_mask:0xf bank_mask:0xf
	v_mul_f32_dpp v158, v158, v158 row_shr:1 row_mask:0xf bank_mask:0xf
	v_mul_f32_dpp v159, v159, v159 row_shr:1 row_mask:0xf bank_mask:0xf
	v_mul_f32_dpp v128, v128, v128 row_shr:2 row_mask:0xf bank_mask:0xf
	v_mul_f32_dpp v129, v129, v129 row_shr:2 row_mask:0xf bank_mask:0xf
	v_mul_f32_dpp v130, v130, v130 row_shr:2 row_mask:0xf bank_mask:0xf
	v_mul_f32_dpp v131, v131, v131 row_shr:2 row_mask:0xf bank_mask:0xf
	v_mul_f32_dpp v132, v132, v132 row_shr:2 row_mask:0xf bank_mask:0xf
	v_mul_f32_dpp v133, v133, v133 row_shr:2 row_mask:0xf bank_mask:0xf
	v_mul_f32_dpp v134, v134, v134 row_shr:2 row_mask:0xf bank_mask:0xf
	v_mul_f32_dpp v135, v135, v135 row_shr:2 row_mask:0xf bank_mask:0xf
	v_mul_f32_dpp v136, v136, v136 row_shr:2 row_mask:0xf bank_mask:0xf
	s_add_u32 m0, s71, 4096
	s_nop 0
	global_load_lds_dwordx4 v228, s[30:31]
	v_mul_f32_dpp v137, v137, v137 row_shr:2 row_mask:0xf bank_mask:0xf
	v_mul_f32_dpp v138, v138, v138 row_shr:2 row_mask:0xf bank_mask:0xf
	v_mul_f32_dpp v139, v139, v139 row_shr:2 row_mask:0xf bank_mask:0xf
	v_mul_f32_dpp v140, v140, v140 row_shr:2 row_mask:0xf bank_mask:0xf
	v_mul_f32_dpp v141, v141, v141 row_shr:2 row_mask:0xf bank_mask:0xf
	v_mul_f32_dpp v142, v142, v142 row_shr:2 row_mask:0xf bank_mask:0xf
	v_mul_f32_dpp v143, v143, v143 row_shr:2 row_mask:0xf bank_mask:0xf
	v_mul_f32_dpp v144, v144, v144 row_shr:2 row_mask:0xf bank_mask:0xf
	v_mul_f32_dpp v145, v145, v145 row_shr:2 row_mask:0xf bank_mask:0xf
	v_mul_f32_dpp v146, v146, v146 row_shr:2 row_mask:0xf bank_mask:0xf
	v_mul_f32_dpp v147, v147, v147 row_shr:2 row_mask:0xf bank_mask:0xf
	v_mul_f32_dpp v148, v148, v148 row_shr:2 row_mask:0xf bank_mask:0xf
	v_mul_f32_dpp v149, v149, v149 row_shr:2 row_mask:0xf bank_mask:0xf
	v_mul_f32_dpp v150, v150, v150 row_shr:2 row_mask:0xf bank_mask:0xf
	v_mul_f32_dpp v151, v151, v151 row_shr:2 row_mask:0xf bank_mask:0xf
	v_mul_f32_dpp v152, v152, v152 row_shr:2 row_mask:0xf bank_mask:0xf
	v_mul_f32_dpp v153, v153, v153 row_shr:2 row_mask:0xf bank_mask:0xf
	v_mul_f32_dpp v154, v154, v154 row_shr:2 row_mask:0xf bank_mask:0xf
	v_mul_f32_dpp v155, v155, v155 row_shr:2 row_mask:0xf bank_mask:0xf
	v_mul_f32_dpp v156, v156, v156 row_shr:2 row_mask:0xf bank_mask:0xf
	v_mul_f32_dpp v157, v157, v157 row_shr:2 row_mask:0xf bank_mask:0xf
	s_add_u32 m0, s71, 1024
	s_nop 0
	global_load_lds_dwordx4 v230, s[14:15]
	v_mul_f32_dpp v158, v158, v158 row_shr:2 row_mask:0xf bank_mask:0xf
	v_mul_f32_dpp v159, v159, v159 row_shr:2 row_mask:0xf bank_mask:0xf
	v_mul_f32_dpp v128, v128, v128 row_shr:4 row_mask:0xf bank_mask:0xf
	v_mul_f32_dpp v129, v129, v129 row_shr:4 row_mask:0xf bank_mask:0xf
	v_mul_f32_dpp v130, v130, v130 row_shr:4 row_mask:0xf bank_mask:0xf
	v_mul_f32_dpp v131, v131, v131 row_shr:4 row_mask:0xf bank_mask:0xf
	v_mul_f32_dpp v132, v132, v132 row_shr:4 row_mask:0xf bank_mask:0xf
	v_mul_f32_dpp v133, v133, v133 row_shr:4 row_mask:0xf bank_mask:0xf
	v_mul_f32_dpp v134, v134, v134 row_shr:4 row_mask:0xf bank_mask:0xf
	v_mul_f32_dpp v135, v135, v135 row_shr:4 row_mask:0xf bank_mask:0xf
	v_mul_f32_dpp v136, v136, v136 row_shr:4 row_mask:0xf bank_mask:0xf
	v_mul_f32_dpp v137, v137, v137 row_shr:4 row_mask:0xf bank_mask:0xf
	v_mul_f32_dpp v138, v138, v138 row_shr:4 row_mask:0xf bank_mask:0xf
	v_mul_f32_dpp v139, v139, v139 row_shr:4 row_mask:0xf bank_mask:0xf
	v_mul_f32_dpp v140, v140, v140 row_shr:4 row_mask:0xf bank_mask:0xf
	v_mul_f32_dpp v141, v141, v141 row_shr:4 row_mask:0xf bank_mask:0xf
	v_mul_f32_dpp v142, v142, v142 row_shr:4 row_mask:0xf bank_mask:0xf
	v_mul_f32_dpp v143, v143, v143 row_shr:4 row_mask:0xf bank_mask:0xf
	v_mul_f32_dpp v144, v144, v144 row_shr:4 row_mask:0xf bank_mask:0xf
	v_mul_f32_dpp v145, v145, v145 row_shr:4 row_mask:0xf bank_mask:0xf
	v_mul_f32_dpp v146, v146, v146 row_shr:4 row_mask:0xf bank_mask:0xf
	s_add_u32 m0, s71, 5120
	s_nop 0
	global_load_lds_dwordx4 v230, s[30:31]
	v_mul_f32_dpp v147, v147, v147 row_shr:4 row_mask:0xf bank_mask:0xf
	v_mul_f32_dpp v148, v148, v148 row_shr:4 row_mask:0xf bank_mask:0xf
	v_mul_f32_dpp v149, v149, v149 row_shr:4 row_mask:0xf bank_mask:0xf
	v_mul_f32_dpp v150, v150, v150 row_shr:4 row_mask:0xf bank_mask:0xf
	v_mul_f32_dpp v151, v151, v151 row_shr:4 row_mask:0xf bank_mask:0xf
	v_mul_f32_dpp v152, v152, v152 row_shr:4 row_mask:0xf bank_mask:0xf
	v_mul_f32_dpp v153, v153, v153 row_shr:4 row_mask:0xf bank_mask:0xf
	v_mul_f32_dpp v154, v154, v154 row_shr:4 row_mask:0xf bank_mask:0xf
	v_mul_f32_dpp v155, v155, v155 row_shr:4 row_mask:0xf bank_mask:0xf
	v_mul_f32_dpp v156, v156, v156 row_shr:4 row_mask:0xf bank_mask:0xf
	v_mul_f32_dpp v157, v157, v157 row_shr:4 row_mask:0xf bank_mask:0xf
	v_mul_f32_dpp v158, v158, v158 row_shr:4 row_mask:0xf bank_mask:0xf
	v_mul_f32_dpp v159, v159, v159 row_shr:4 row_mask:0xf bank_mask:0xf
	v_mul_f32_dpp v128, v128, v128 row_shr:8 row_mask:0xf bank_mask:0xf
	v_mul_f32_dpp v129, v129, v129 row_shr:8 row_mask:0xf bank_mask:0xf
	v_mul_f32_dpp v130, v130, v130 row_shr:8 row_mask:0xf bank_mask:0xf
	v_mul_f32_dpp v131, v131, v131 row_shr:8 row_mask:0xf bank_mask:0xf
	v_mul_f32_dpp v132, v132, v132 row_shr:8 row_mask:0xf bank_mask:0xf
	v_mul_f32_dpp v133, v133, v133 row_shr:8 row_mask:0xf bank_mask:0xf
	v_mul_f32_dpp v134, v134, v134 row_shr:8 row_mask:0xf bank_mask:0xf
	v_mul_f32_dpp v135, v135, v135 row_shr:8 row_mask:0xf bank_mask:0xf
	s_add_u32 m0, s71, 2048
	s_nop 0
	global_load_lds_dwordx4 v231, s[14:15]
	v_mul_f32_dpp v136, v136, v136 row_shr:8 row_mask:0xf bank_mask:0xf
	v_mul_f32_dpp v137, v137, v137 row_shr:8 row_mask:0xf bank_mask:0xf
	v_mul_f32_dpp v138, v138, v138 row_shr:8 row_mask:0xf bank_mask:0xf
	v_mul_f32_dpp v139, v139, v139 row_shr:8 row_mask:0xf bank_mask:0xf
	v_mul_f32_dpp v140, v140, v140 row_shr:8 row_mask:0xf bank_mask:0xf
	v_mul_f32_dpp v141, v141, v141 row_shr:8 row_mask:0xf bank_mask:0xf
	v_mul_f32_dpp v142, v142, v142 row_shr:8 row_mask:0xf bank_mask:0xf
	v_mul_f32_dpp v143, v143, v143 row_shr:8 row_mask:0xf bank_mask:0xf
	v_mul_f32_dpp v144, v144, v144 row_shr:8 row_mask:0xf bank_mask:0xf
	v_mul_f32_dpp v145, v145, v145 row_shr:8 row_mask:0xf bank_mask:0xf
	v_mul_f32_dpp v146, v146, v146 row_shr:8 row_mask:0xf bank_mask:0xf
	v_mul_f32_dpp v147, v147, v147 row_shr:8 row_mask:0xf bank_mask:0xf
	v_mul_f32_dpp v148, v148, v148 row_shr:8 row_mask:0xf bank_mask:0xf
	v_mul_f32_dpp v149, v149, v149 row_shr:8 row_mask:0xf bank_mask:0xf
	v_mul_f32_dpp v150, v150, v150 row_shr:8 row_mask:0xf bank_mask:0xf
	v_mul_f32_dpp v151, v151, v151 row_shr:8 row_mask:0xf bank_mask:0xf
	v_mul_f32_dpp v152, v152, v152 row_shr:8 row_mask:0xf bank_mask:0xf
	v_mul_f32_dpp v153, v153, v153 row_shr:8 row_mask:0xf bank_mask:0xf
	v_mul_f32_dpp v154, v154, v154 row_shr:8 row_mask:0xf bank_mask:0xf
	v_mul_f32_dpp v155, v155, v155 row_shr:8 row_mask:0xf bank_mask:0xf
	v_mul_f32_dpp v156, v156, v156 row_shr:8 row_mask:0xf bank_mask:0xf
	s_add_u32 m0, s71, 6144
	s_nop 0
	global_load_lds_dwordx4 v231, s[30:31]
	v_mul_f32_dpp v157, v157, v157 row_shr:8 row_mask:0xf bank_mask:0xf
	v_mul_f32_dpp v158, v158, v158 row_shr:8 row_mask:0xf bank_mask:0xf
	v_mul_f32_dpp v159, v159, v159 row_shr:8 row_mask:0xf bank_mask:0xf
	v_mul_f32_dpp v128, v128, v128 row_bcast:15 row_mask:0xa bank_mask:0xf
	v_mul_f32_dpp v129, v129, v129 row_bcast:15 row_mask:0xa bank_mask:0xf
	v_mul_f32_dpp v130, v130, v130 row_bcast:15 row_mask:0xa bank_mask:0xf
	v_mul_f32_dpp v131, v131, v131 row_bcast:15 row_mask:0xa bank_mask:0xf
	v_mul_f32_dpp v132, v132, v132 row_bcast:15 row_mask:0xa bank_mask:0xf
	v_mul_f32_dpp v133, v133, v133 row_bcast:15 row_mask:0xa bank_mask:0xf
	v_mul_f32_dpp v134, v134, v134 row_bcast:15 row_mask:0xa bank_mask:0xf
	v_mul_f32_dpp v135, v135, v135 row_bcast:15 row_mask:0xa bank_mask:0xf
	v_mul_f32_dpp v136, v136, v136 row_bcast:15 row_mask:0xa bank_mask:0xf
	v_mul_f32_dpp v137, v137, v137 row_bcast:15 row_mask:0xa bank_mask:0xf
	v_mul_f32_dpp v138, v138, v138 row_bcast:15 row_mask:0xa bank_mask:0xf
	v_mul_f32_dpp v139, v139, v139 row_bcast:15 row_mask:0xa bank_mask:0xf
	v_mul_f32_dpp v140, v140, v140 row_bcast:15 row_mask:0xa bank_mask:0xf
	v_mul_f32_dpp v141, v141, v141 row_bcast:15 row_mask:0xa bank_mask:0xf
	v_mul_f32_dpp v142, v142, v142 row_bcast:15 row_mask:0xa bank_mask:0xf
	v_mul_f32_dpp v143, v143, v143 row_bcast:15 row_mask:0xa bank_mask:0xf
	v_mul_f32_dpp v144, v144, v144 row_bcast:15 row_mask:0xa bank_mask:0xf
	v_mul_f32_dpp v145, v145, v145 row_bcast:15 row_mask:0xa bank_mask:0xf
	s_add_u32 m0, s71, 3072
	s_nop 0
	global_load_lds_dwordx4 v232, s[14:15]
	v_mul_f32_dpp v146, v146, v146 row_bcast:15 row_mask:0xa bank_mask:0xf
	v_mul_f32_dpp v147, v147, v147 row_bcast:15 row_mask:0xa bank_mask:0xf
	v_mul_f32_dpp v148, v148, v148 row_bcast:15 row_mask:0xa bank_mask:0xf
	v_mul_f32_dpp v149, v149, v149 row_bcast:15 row_mask:0xa bank_mask:0xf
	v_mul_f32_dpp v150, v150, v150 row_bcast:15 row_mask:0xa bank_mask:0xf
	v_mul_f32_dpp v151, v151, v151 row_bcast:15 row_mask:0xa bank_mask:0xf
	v_mul_f32_dpp v152, v152, v152 row_bcast:15 row_mask:0xa bank_mask:0xf
	v_mul_f32_dpp v153, v153, v153 row_bcast:15 row_mask:0xa bank_mask:0xf
	v_mul_f32_dpp v154, v154, v154 row_bcast:15 row_mask:0xa bank_mask:0xf
	v_mul_f32_dpp v155, v155, v155 row_bcast:15 row_mask:0xa bank_mask:0xf
	v_mul_f32_dpp v156, v156, v156 row_bcast:15 row_mask:0xa bank_mask:0xf
	v_mul_f32_dpp v157, v157, v157 row_bcast:15 row_mask:0xa bank_mask:0xf
	v_mul_f32_dpp v158, v158, v158 row_bcast:15 row_mask:0xa bank_mask:0xf
	v_mul_f32_dpp v159, v159, v159 row_bcast:15 row_mask:0xa bank_mask:0xf
	v_mul_f32_dpp v128, v128, v128 row_bcast:31 row_mask:0xc bank_mask:0xf
	v_mul_f32_dpp v129, v129, v129 row_bcast:31 row_mask:0xc bank_mask:0xf
	v_mul_f32_dpp v130, v130, v130 row_bcast:31 row_mask:0xc bank_mask:0xf
	v_mul_f32_dpp v131, v131, v131 row_bcast:31 row_mask:0xc bank_mask:0xf
	v_mul_f32_dpp v132, v132, v132 row_bcast:31 row_mask:0xc bank_mask:0xf
	v_mul_f32_dpp v133, v133, v133 row_bcast:31 row_mask:0xc bank_mask:0xf
	v_mul_f32_dpp v134, v134, v134 row_bcast:31 row_mask:0xc bank_mask:0xf
	s_add_u32 m0, s71, 7168
	s_nop 0
	global_load_lds_dwordx4 v232, s[30:31]
	v_add_u32_e32 v228, s76, v228
	v_add_u32_e32 v230, s76, v230
	v_add_u32_e32 v231, s76, v231
	v_add_u32_e32 v232, s76, v232
	v_mul_f32_dpp v135, v135, v135 row_bcast:31 row_mask:0xc bank_mask:0xf
	v_mul_f32_dpp v136, v136, v136 row_bcast:31 row_mask:0xc bank_mask:0xf
	v_mul_f32_dpp v137, v137, v137 row_bcast:31 row_mask:0xc bank_mask:0xf
	v_mul_f32_dpp v138, v138, v138 row_bcast:31 row_mask:0xc bank_mask:0xf
	v_mul_f32_dpp v139, v139, v139 row_bcast:31 row_mask:0xc bank_mask:0xf
	v_mul_f32_dpp v140, v140, v140 row_bcast:31 row_mask:0xc bank_mask:0xf
	v_mul_f32_dpp v141, v141, v141 row_bcast:31 row_mask:0xc bank_mask:0xf
	v_mul_f32_dpp v142, v142, v142 row_bcast:31 row_mask:0xc bank_mask:0xf
	v_mul_f32_dpp v143, v143, v143 row_bcast:31 row_mask:0xc bank_mask:0xf
	v_mul_f32_dpp v144, v144, v144 row_bcast:31 row_mask:0xc bank_mask:0xf
	v_mul_f32_dpp v145, v145, v145 row_bcast:31 row_mask:0xc bank_mask:0xf
	v_mul_f32_dpp v146, v146, v146 row_bcast:31 row_mask:0xc bank_mask:0xf
	v_mul_f32_dpp v147, v147, v147 row_bcast:31 row_mask:0xc bank_mask:0xf
	v_mul_f32_dpp v148, v148, v148 row_bcast:31 row_mask:0xc bank_mask:0xf
	v_mul_f32_dpp v149, v149, v149 row_bcast:31 row_mask:0xc bank_mask:0xf
	v_mul_f32_dpp v150, v150, v150 row_bcast:31 row_mask:0xc bank_mask:0xf
	v_mul_f32_dpp v151, v151, v151 row_bcast:31 row_mask:0xc bank_mask:0xf
	v_mul_f32_dpp v152, v152, v152 row_bcast:31 row_mask:0xc bank_mask:0xf
	v_mul_f32_dpp v153, v153, v153 row_bcast:31 row_mask:0xc bank_mask:0xf
	v_mul_f32_dpp v154, v154, v154 row_bcast:31 row_mask:0xc bank_mask:0xf
	v_mul_f32_dpp v155, v155, v155 row_bcast:31 row_mask:0xc bank_mask:0xf
	v_mul_f32_dpp v156, v156, v156 row_bcast:31 row_mask:0xc bank_mask:0xf
	v_mul_f32_dpp v157, v157, v157 row_bcast:31 row_mask:0xc bank_mask:0xf
	v_mul_f32_dpp v158, v158, v158 row_bcast:31 row_mask:0xc bank_mask:0xf
	v_mul_f32_dpp v159, v159, v159 row_bcast:31 row_mask:0xc bank_mask:0xf
	s_mov_b32 exec_lo, 0
	s_brev_b32 exec_hi, 1
	ds_write_b128 v247, v[128:131] offset:0
	ds_write_b128 v247, v[132:135] offset:16
	ds_write_b128 v247, v[136:139] offset:32
	ds_write_b128 v247, v[140:143] offset:48
	ds_write_b128 v247, v[144:147] offset:64
	ds_write_b128 v247, v[148:151] offset:80
	ds_write_b128 v247, v[152:155] offset:96
	ds_write_b128 v247, v[156:159] offset:112
	s_mov_b64 exec, -1
	v_rcp_f32_e32 v220, v128
	v_rcp_f32_e32 v221, v129
	v_lshlrev_b32_e32 v218, 16, v0
	v_and_b32_e32 v219, 0xffff0000, v0
	v_pk_mul_f32 v[218:219], v[128:129], v[218:219]
	v_pk_mul_f32 v[220:221], v[220:221], v[96:97]
	v_cvt_pk_bf16_f32 v202, v218, v219
	v_cvt_pk_bf16_f32 v184, v220, v221
	v_rcp_f32_e32 v220, v130
	v_rcp_f32_e32 v221, v131
	v_lshlrev_b32_e32 v218, 16, v1
	v_and_b32_e32 v219, 0xffff0000, v1
	v_pk_mul_f32 v[218:219], v[130:131], v[218:219]
	v_pk_mul_f32 v[220:221], v[220:221], v[98:99]
	v_cvt_pk_bf16_f32 v203, v218, v219
	v_cvt_pk_bf16_f32 v185, v220, v221
	v_rcp_f32_e32 v220, v132
	v_rcp_f32_e32 v221, v133
	v_lshlrev_b32_e32 v218, 16, v2
	v_and_b32_e32 v219, 0xffff0000, v2
	v_pk_mul_f32 v[218:219], v[132:133], v[218:219]
	v_pk_mul_f32 v[220:221], v[220:221], v[100:101]
	v_cvt_pk_bf16_f32 v204, v218, v219
	v_cvt_pk_bf16_f32 v186, v220, v221
	v_rcp_f32_e32 v220, v134
	v_rcp_f32_e32 v221, v135
	v_lshlrev_b32_e32 v218, 16, v3
	v_and_b32_e32 v219, 0xffff0000, v3
	v_pk_mul_f32 v[218:219], v[134:135], v[218:219]
	v_pk_mul_f32 v[220:221], v[220:221], v[102:103]
	v_cvt_pk_bf16_f32 v205, v218, v219
	v_cvt_pk_bf16_f32 v187, v220, v221
	v_rcp_f32_e32 v220, v136
	v_rcp_f32_e32 v221, v137
	v_lshlrev_b32_e32 v218, 16, v4
	v_and_b32_e32 v219, 0xffff0000, v4
	v_pk_mul_f32 v[218:219], v[136:137], v[218:219]
	v_pk_mul_f32 v[220:221], v[220:221], v[104:105]
	v_cvt_pk_bf16_f32 v206, v218, v219
	v_cvt_pk_bf16_f32 v188, v220, v221
	v_rcp_f32_e32 v220, v138
	v_rcp_f32_e32 v221, v139
	v_lshlrev_b32_e32 v218, 16, v5
	v_and_b32_e32 v219, 0xffff0000, v5
	v_pk_mul_f32 v[218:219], v[138:139], v[218:219]
	v_pk_mul_f32 v[220:221], v[220:221], v[106:107]
	v_cvt_pk_bf16_f32 v207, v218, v219
	v_cvt_pk_bf16_f32 v189, v220, v221
	v_rcp_f32_e32 v220, v140
	v_rcp_f32_e32 v221, v141
	v_lshlrev_b32_e32 v218, 16, v6
	v_and_b32_e32 v219, 0xffff0000, v6
	v_pk_mul_f32 v[218:219], v[140:141], v[218:219]
	v_pk_mul_f32 v[220:221], v[220:221], v[108:109]
	v_cvt_pk_bf16_f32 v208, v218, v219
	v_cvt_pk_bf16_f32 v190, v220, v221
	v_rcp_f32_e32 v220, v142
	v_rcp_f32_e32 v221, v143
	v_lshlrev_b32_e32 v218, 16, v7
	v_and_b32_e32 v219, 0xffff0000, v7
	v_pk_mul_f32 v[218:219], v[142:143], v[218:219]
	v_pk_mul_f32 v[220:221], v[220:221], v[110:111]
	v_cvt_pk_bf16_f32 v209, v218, v219
	v_cvt_pk_bf16_f32 v191, v220, v221
	v_rcp_f32_e32 v220, v144
	v_rcp_f32_e32 v221, v145
	v_lshlrev_b32_e32 v218, 16, v8
	v_and_b32_e32 v219, 0xffff0000, v8
	v_pk_mul_f32 v[218:219], v[144:145], v[218:219]
	v_pk_mul_f32 v[220:221], v[220:221], v[112:113]
	v_cvt_pk_bf16_f32 v210, v218, v219
	v_cvt_pk_bf16_f32 v192, v220, v221
	v_rcp_f32_e32 v220, v146
	v_rcp_f32_e32 v221, v147
	v_lshlrev_b32_e32 v218, 16, v9
	v_and_b32_e32 v219, 0xffff0000, v9
	v_pk_mul_f32 v[218:219], v[146:147], v[218:219]
	v_pk_mul_f32 v[220:221], v[220:221], v[114:115]
	v_cvt_pk_bf16_f32 v211, v218, v219
	v_cvt_pk_bf16_f32 v193, v220, v221
	v_rcp_f32_e32 v220, v148
	v_rcp_f32_e32 v221, v149
	v_lshlrev_b32_e32 v218, 16, v10
	v_and_b32_e32 v219, 0xffff0000, v10
	v_pk_mul_f32 v[218:219], v[148:149], v[218:219]
	v_pk_mul_f32 v[220:221], v[220:221], v[116:117]
	v_cvt_pk_bf16_f32 v212, v218, v219
	v_cvt_pk_bf16_f32 v194, v220, v221
	v_rcp_f32_e32 v220, v150
	v_rcp_f32_e32 v221, v151
	v_lshlrev_b32_e32 v218, 16, v11
	v_and_b32_e32 v219, 0xffff0000, v11
	v_pk_mul_f32 v[218:219], v[150:151], v[218:219]
	v_pk_mul_f32 v[220:221], v[220:221], v[118:119]
	v_cvt_pk_bf16_f32 v213, v218, v219
	v_cvt_pk_bf16_f32 v195, v220, v221
	v_rcp_f32_e32 v220, v152
	v_rcp_f32_e32 v221, v153
	v_lshlrev_b32_e32 v218, 16, v12
	v_and_b32_e32 v219, 0xffff0000, v12
	v_pk_mul_f32 v[218:219], v[152:153], v[218:219]
	v_pk_mul_f32 v[220:221], v[220:221], v[120:121]
	v_cvt_pk_bf16_f32 v214, v218, v219
	v_cvt_pk_bf16_f32 v196, v220, v221
	v_rcp_f32_e32 v220, v154
	v_rcp_f32_e32 v221, v155
	v_lshlrev_b32_e32 v218, 16, v13
	v_and_b32_e32 v219, 0xffff0000, v13
	v_pk_mul_f32 v[218:219], v[154:155], v[218:219]
	v_pk_mul_f32 v[220:221], v[220:221], v[122:123]
	v_cvt_pk_bf16_f32 v215, v218, v219
	v_cvt_pk_bf16_f32 v197, v220, v221
	v_rcp_f32_e32 v220, v156
	v_rcp_f32_e32 v221, v157
	v_lshlrev_b32_e32 v218, 16, v14
	v_and_b32_e32 v219, 0xffff0000, v14
	v_pk_mul_f32 v[218:219], v[156:157], v[218:219]
	v_pk_mul_f32 v[220:221], v[220:221], v[124:125]
	v_cvt_pk_bf16_f32 v216, v218, v219
	v_cvt_pk_bf16_f32 v198, v220, v221
	v_rcp_f32_e32 v220, v158
	v_rcp_f32_e32 v221, v159
	v_lshlrev_b32_e32 v218, 16, v15
	v_and_b32_e32 v219, 0xffff0000, v15
	v_pk_mul_f32 v[218:219], v[158:159], v[218:219]
	v_pk_mul_f32 v[220:221], v[220:221], v[126:127]
	v_cvt_pk_bf16_f32 v217, v218, v219
	v_cvt_pk_bf16_f32 v199, v220, v221
	ds_write_b128 v222, v[184:187] offset:1024
	ds_write_b128 v223, v[188:191] offset:1024
	ds_write_b128 v224, v[192:195] offset:1024
	ds_write_b128 v225, v[196:199] offset:1024
	ds_write_b128 v226, v[202:205]
	ds_write_b128 v226, v[206:209] offset:16
	ds_write_b128 v226, v[210:213] offset:32
	ds_write_b128 v226, v[214:217] offset:48
	s_waitcnt vmcnt(8)
	s_waitcnt lgkmcnt(0)
	s_barrier
	s_waitcnt vmcnt(0)
	ds_read_b128 v[234:237], v248
	ds_read_b128 v[238:241], v249
	ds_read_b128 v[242:245], v250
	ds_read_b128 v[168:171], v251
	ds_read_b128 v[0:3], v248 offset:4096
	ds_read_b128 v[4:7], v249 offset:4096
	ds_read_b128 v[8:11], v250 offset:4096
	ds_read_b128 v[12:15], v251 offset:4096
	s_cmp_eq_u32 s70, 31
	s_cselect_b32 s76, 0, s33
	s_waitcnt lgkmcnt(4)
	s_add_u32 m0, s72, 50176
	s_nop 0
	global_load_lds_dwordx4 v252, s[34:35]
	v_lshlrev_b32_e32 v96, 16, v234
	v_and_b32_e32 v97, 0xffff0000, v234
	v_lshlrev_b32_e32 v98, 16, v235
	v_and_b32_e32 v99, 0xffff0000, v235
	v_lshlrev_b32_e32 v100, 16, v236
	v_and_b32_e32 v101, 0xffff0000, v236
	v_lshlrev_b32_e32 v102, 16, v237
	v_and_b32_e32 v103, 0xffff0000, v237
	v_lshlrev_b32_e32 v104, 16, v238
	v_and_b32_e32 v105, 0xffff0000, v238
	v_lshlrev_b32_e32 v106, 16, v239
	v_and_b32_e32 v107, 0xffff0000, v239
	v_lshlrev_b32_e32 v108, 16, v240
	v_and_b32_e32 v109, 0xffff0000, v240
	v_lshlrev_b32_e32 v110, 16, v241
	v_and_b32_e32 v111, 0xffff0000, v241
	v_lshlrev_b32_e32 v112, 16, v242
	v_and_b32_e32 v113, 0xffff0000, v242
	v_lshlrev_b32_e32 v114, 16, v243
	v_and_b32_e32 v115, 0xffff0000, v243
	v_lshlrev_b32_e32 v116, 16, v244
	s_add_u32 m0, s72, 51200
	s_nop 0
	global_load_lds_dwordx4 v253, s[34:35]
	v_and_b32_e32 v117, 0xffff0000, v244
	v_lshlrev_b32_e32 v118, 16, v245
	v_and_b32_e32 v119, 0xffff0000, v245
	v_lshlrev_b32_e32 v120, 16, v168
	v_and_b32_e32 v121, 0xffff0000, v168
	v_lshlrev_b32_e32 v122, 16, v169
	v_and_b32_e32 v123, 0xffff0000, v169
	v_lshlrev_b32_e32 v124, 16, v170
	v_and_b32_e32 v125, 0xffff0000, v170
	v_lshlrev_b32_e32 v126, 16, v171
	v_and_b32_e32 v127, 0xffff0000, v171
	s_waitcnt lgkmcnt(0)
	v_sub_f32_e32 v128, 1.0, v96
	v_sub_f32_e32 v129, 1.0, v97
	v_sub_f32_e32 v130, 1.0, v98
	v_sub_f32_e32 v131, 1.0, v99
	v_sub_f32_e32 v132, 1.0, v100
	v_sub_f32_e32 v133, 1.0, v101
	v_sub_f32_e32 v134, 1.0, v102
	v_sub_f32_e32 v135, 1.0, v103
	v_sub_f32_e32 v136, 1.0, v104
	v_sub_f32_e32 v137, 1.0, v105
	s_add_u32 m0, s72, 52224
	s_nop 0
	global_load_lds_dwordx4 v254, s[34:35]
	v_sub_f32_e32 v138, 1.0, v106
	v_sub_f32_e32 v139, 1.0, v107
	v_sub_f32_e32 v140, 1.0, v108
	v_sub_f32_e32 v141, 1.0, v109
	v_sub_f32_e32 v142, 1.0, v110
	v_sub_f32_e32 v143, 1.0, v111
	v_sub_f32_e32 v144, 1.0, v112
	v_sub_f32_e32 v145, 1.0, v113
	v_sub_f32_e32 v146, 1.0, v114
	v_sub_f32_e32 v147, 1.0, v115
	v_sub_f32_e32 v148, 1.0, v116
	v_sub_f32_e32 v149, 1.0, v117
	v_sub_f32_e32 v150, 1.0, v118
	v_sub_f32_e32 v151, 1.0, v119
	v_sub_f32_e32 v152, 1.0, v120
	v_sub_f32_e32 v153, 1.0, v121
	v_sub_f32_e32 v154, 1.0, v122
	v_sub_f32_e32 v155, 1.0, v123
	v_sub_f32_e32 v156, 1.0, v124
	v_sub_f32_e32 v157, 1.0, v125
	v_sub_f32_e32 v158, 1.0, v126
	s_add_u32 m0, s72, 53248
	s_nop 0
	global_load_lds_dwordx4 v255, s[34:35]
	v_add_u32_e32 v252, s33, v252
	v_add_u32_e32 v253, s33, v253
	v_add_u32_e32 v254, s33, v254
	v_add_u32_e32 v255, s33, v255
	v_sub_f32_e32 v159, 1.0, v127
	v_mul_f32_dpp v128, v128, v128 row_shr:1 row_mask:0xf bank_mask:0xf
	v_mul_f32_dpp v129, v129, v129 row_shr:1 row_mask:0xf bank_mask:0xf
	v_mul_f32_dpp v130, v130, v130 row_shr:1 row_mask:0xf bank_mask:0xf
	v_mul_f32_dpp v131, v131, v131 row_shr:1 row_mask:0xf bank_mask:0xf
	v_mul_f32_dpp v132, v132, v132 row_shr:1 row_mask:0xf bank_mask:0xf
	v_mul_f32_dpp v133, v133, v133 row_shr:1 row_mask:0xf bank_mask:0xf
	v_mul_f32_dpp v134, v134, v134 row_shr:1 row_mask:0xf bank_mask:0xf
	v_mul_f32_dpp v135, v135, v135 row_shr:1 row_mask:0xf bank_mask:0xf
	v_mul_f32_dpp v136, v136, v136 row_shr:1 row_mask:0xf bank_mask:0xf
	v_mul_f32_dpp v137, v137, v137 row_shr:1 row_mask:0xf bank_mask:0xf
	v_mul_f32_dpp v138, v138, v138 row_shr:1 row_mask:0xf bank_mask:0xf
	v_mul_f32_dpp v139, v139, v139 row_shr:1 row_mask:0xf bank_mask:0xf
	v_mul_f32_dpp v140, v140, v140 row_shr:1 row_mask:0xf bank_mask:0xf
	v_mul_f32_dpp v141, v141, v141 row_shr:1 row_mask:0xf bank_mask:0xf
	v_mul_f32_dpp v142, v142, v142 row_shr:1 row_mask:0xf bank_mask:0xf
	v_mul_f32_dpp v143, v143, v143 row_shr:1 row_mask:0xf bank_mask:0xf
	v_mul_f32_dpp v144, v144, v144 row_shr:1 row_mask:0xf bank_mask:0xf
	v_mul_f32_dpp v145, v145, v145 row_shr:1 row_mask:0xf bank_mask:0xf
	v_mul_f32_dpp v146, v146, v146 row_shr:1 row_mask:0xf bank_mask:0xf
	v_mul_f32_dpp v147, v147, v147 row_shr:1 row_mask:0xf bank_mask:0xf
	s_add_u32 m0, s71, 0
	s_nop 0
	global_load_lds_dwordx4 v228, s[14:15]
	v_mul_f32_dpp v148, v148, v148 row_shr:1 row_mask:0xf bank_mask:0xf
	v_mul_f32_dpp v149, v149, v149 row_shr:1 row_mask:0xf bank_mask:0xf
	v_mul_f32_dpp v150, v150, v150 row_shr:1 row_mask:0xf bank_mask:0xf
	v_mul_f32_dpp v151, v151, v151 row_shr:1 row_mask:0xf bank_mask:0xf
	v_mul_f32_dpp v152, v152, v152 row_shr:1 row_mask:0xf bank_mask:0xf
	v_mul_f32_dpp v153, v153, v153 row_shr:1 row_mask:0xf bank_mask:0xf
	v_mul_f32_dpp v154, v154, v154 row_shr:1 row_mask:0xf bank_mask:0xf
	v_mul_f32_dpp v155, v155, v155 row_shr:1 row_mask:0xf bank_mask:0xf
	v_mul_f32_dpp v156, v156, v156 row_shr:1 row_mask:0xf bank_mask:0xf
	v_mul_f32_dpp v157, v157, v157 row_shr:1 row_mask:0xf bank_mask:0xf
	v_mul_f32_dpp v158, v158, v158 row_shr:1 row_mask:0xf bank_mask:0xf
	v_mul_f32_dpp v159, v159, v159 row_shr:1 row_mask:0xf bank_mask:0xf
	v_mul_f32_dpp v128, v128, v128 row_shr:2 row_mask:0xf bank_mask:0xf
	v_mul_f32_dpp v129, v129, v129 row_shr:2 row_mask:0xf bank_mask:0xf
	v_mul_f32_dpp v130, v130, v130 row_shr:2 row_mask:0xf bank_mask:0xf
	v_mul_f32_dpp v131, v131, v131 row_shr:2 row_mask:0xf bank_mask:0xf
	v_mul_f32_dpp v132, v132, v132 row_shr:2 row_mask:0xf bank_mask:0xf
	v_mul_f32_dpp v133, v133, v133 row_shr:2 row_mask:0xf bank_mask:0xf
	v_mul_f32_dpp v134, v134, v134 row_shr:2 row_mask:0xf bank_mask:0xf
	v_mul_f32_dpp v135, v135, v135 row_shr:2 row_mask:0xf bank_mask:0xf
	v_mul_f32_dpp v136, v136, v136 row_shr:2 row_mask:0xf bank_mask:0xf
	s_add_u32 m0, s71, 4096
	s_nop 0
	global_load_lds_dwordx4 v228, s[30:31]
	v_mul_f32_dpp v137, v137, v137 row_shr:2 row_mask:0xf bank_mask:0xf
	v_mul_f32_dpp v138, v138, v138 row_shr:2 row_mask:0xf bank_mask:0xf
	v_mul_f32_dpp v139, v139, v139 row_shr:2 row_mask:0xf bank_mask:0xf
	v_mul_f32_dpp v140, v140, v140 row_shr:2 row_mask:0xf bank_mask:0xf
	v_mul_f32_dpp v141, v141, v141 row_shr:2 row_mask:0xf bank_mask:0xf
	v_mul_f32_dpp v142, v142, v142 row_shr:2 row_mask:0xf bank_mask:0xf
	v_mul_f32_dpp v143, v143, v143 row_shr:2 row_mask:0xf bank_mask:0xf
	v_mul_f32_dpp v144, v144, v144 row_shr:2 row_mask:0xf bank_mask:0xf
	v_mul_f32_dpp v145, v145, v145 row_shr:2 row_mask:0xf bank_mask:0xf
	v_mul_f32_dpp v146, v146, v146 row_shr:2 row_mask:0xf bank_mask:0xf
	v_mul_f32_dpp v147, v147, v147 row_shr:2 row_mask:0xf bank_mask:0xf
	v_mul_f32_dpp v148, v148, v148 row_shr:2 row_mask:0xf bank_mask:0xf
	v_mul_f32_dpp v149, v149, v149 row_shr:2 row_mask:0xf bank_mask:0xf
	v_mul_f32_dpp v150, v150, v150 row_shr:2 row_mask:0xf bank_mask:0xf
	v_mul_f32_dpp v151, v151, v151 row_shr:2 row_mask:0xf bank_mask:0xf
	v_mul_f32_dpp v152, v152, v152 row_shr:2 row_mask:0xf bank_mask:0xf
	v_mul_f32_dpp v153, v153, v153 row_shr:2 row_mask:0xf bank_mask:0xf
	v_mul_f32_dpp v154, v154, v154 row_shr:2 row_mask:0xf bank_mask:0xf
	v_mul_f32_dpp v155, v155, v155 row_shr:2 row_mask:0xf bank_mask:0xf
	v_mul_f32_dpp v156, v156, v156 row_shr:2 row_mask:0xf bank_mask:0xf
	v_mul_f32_dpp v157, v157, v157 row_shr:2 row_mask:0xf bank_mask:0xf
	s_add_u32 m0, s71, 1024
	s_nop 0
	global_load_lds_dwordx4 v230, s[14:15]
	v_mul_f32_dpp v158, v158, v158 row_shr:2 row_mask:0xf bank_mask:0xf
	v_mul_f32_dpp v159, v159, v159 row_shr:2 row_mask:0xf bank_mask:0xf
	v_mul_f32_dpp v128, v128, v128 row_shr:4 row_mask:0xf bank_mask:0xf
	v_mul_f32_dpp v129, v129, v129 row_shr:4 row_mask:0xf bank_mask:0xf
	v_mul_f32_dpp v130, v130, v130 row_shr:4 row_mask:0xf bank_mask:0xf
	v_mul_f32_dpp v131, v131, v131 row_shr:4 row_mask:0xf bank_mask:0xf
	v_mul_f32_dpp v132, v132, v132 row_shr:4 row_mask:0xf bank_mask:0xf
	v_mul_f32_dpp v133, v133, v133 row_shr:4 row_mask:0xf bank_mask:0xf
	v_mul_f32_dpp v134, v134, v134 row_shr:4 row_mask:0xf bank_mask:0xf
	v_mul_f32_dpp v135, v135, v135 row_shr:4 row_mask:0xf bank_mask:0xf
	v_mul_f32_dpp v136, v136, v136 row_shr:4 row_mask:0xf bank_mask:0xf
	v_mul_f32_dpp v137, v137, v137 row_shr:4 row_mask:0xf bank_mask:0xf
	v_mul_f32_dpp v138, v138, v138 row_shr:4 row_mask:0xf bank_mask:0xf
	v_mul_f32_dpp v139, v139, v139 row_shr:4 row_mask:0xf bank_mask:0xf
	v_mul_f32_dpp v140, v140, v140 row_shr:4 row_mask:0xf bank_mask:0xf
	v_mul_f32_dpp v141, v141, v141 row_shr:4 row_mask:0xf bank_mask:0xf
	v_mul_f32_dpp v142, v142, v142 row_shr:4 row_mask:0xf bank_mask:0xf
	v_mul_f32_dpp v143, v143, v143 row_shr:4 row_mask:0xf bank_mask:0xf
	v_mul_f32_dpp v144, v144, v144 row_shr:4 row_mask:0xf bank_mask:0xf
	v_mul_f32_dpp v145, v145, v145 row_shr:4 row_mask:0xf bank_mask:0xf
	v_mul_f32_dpp v146, v146, v146 row_shr:4 row_mask:0xf bank_mask:0xf
	s_add_u32 m0, s71, 5120
	s_nop 0
	global_load_lds_dwordx4 v230, s[30:31]
	v_mul_f32_dpp v147, v147, v147 row_shr:4 row_mask:0xf bank_mask:0xf
	v_mul_f32_dpp v148, v148, v148 row_shr:4 row_mask:0xf bank_mask:0xf
	v_mul_f32_dpp v149, v149, v149 row_shr:4 row_mask:0xf bank_mask:0xf
	v_mul_f32_dpp v150, v150, v150 row_shr:4 row_mask:0xf bank_mask:0xf
	v_mul_f32_dpp v151, v151, v151 row_shr:4 row_mask:0xf bank_mask:0xf
	v_mul_f32_dpp v152, v152, v152 row_shr:4 row_mask:0xf bank_mask:0xf
	v_mul_f32_dpp v153, v153, v153 row_shr:4 row_mask:0xf bank_mask:0xf
	v_mul_f32_dpp v154, v154, v154 row_shr:4 row_mask:0xf bank_mask:0xf
	v_mul_f32_dpp v155, v155, v155 row_shr:4 row_mask:0xf bank_mask:0xf
	v_mul_f32_dpp v156, v156, v156 row_shr:4 row_mask:0xf bank_mask:0xf
	v_mul_f32_dpp v157, v157, v157 row_shr:4 row_mask:0xf bank_mask:0xf
	v_mul_f32_dpp v158, v158, v158 row_shr:4 row_mask:0xf bank_mask:0xf
	v_mul_f32_dpp v159, v159, v159 row_shr:4 row_mask:0xf bank_mask:0xf
	v_mul_f32_dpp v128, v128, v128 row_shr:8 row_mask:0xf bank_mask:0xf
	v_mul_f32_dpp v129, v129, v129 row_shr:8 row_mask:0xf bank_mask:0xf
	v_mul_f32_dpp v130, v130, v130 row_shr:8 row_mask:0xf bank_mask:0xf
	v_mul_f32_dpp v131, v131, v131 row_shr:8 row_mask:0xf bank_mask:0xf
	v_mul_f32_dpp v132, v132, v132 row_shr:8 row_mask:0xf bank_mask:0xf
	v_mul_f32_dpp v133, v133, v133 row_shr:8 row_mask:0xf bank_mask:0xf
	v_mul_f32_dpp v134, v134, v134 row_shr:8 row_mask:0xf bank_mask:0xf
	v_mul_f32_dpp v135, v135, v135 row_shr:8 row_mask:0xf bank_mask:0xf
	s_add_u32 m0, s71, 2048
	s_nop 0
	global_load_lds_dwordx4 v231, s[14:15]
	v_mul_f32_dpp v136, v136, v136 row_shr:8 row_mask:0xf bank_mask:0xf
	v_mul_f32_dpp v137, v137, v137 row_shr:8 row_mask:0xf bank_mask:0xf
	v_mul_f32_dpp v138, v138, v138 row_shr:8 row_mask:0xf bank_mask:0xf
	v_mul_f32_dpp v139, v139, v139 row_shr:8 row_mask:0xf bank_mask:0xf
	v_mul_f32_dpp v140, v140, v140 row_shr:8 row_mask:0xf bank_mask:0xf
	v_mul_f32_dpp v141, v141, v141 row_shr:8 row_mask:0xf bank_mask:0xf
	v_mul_f32_dpp v142, v142, v142 row_shr:8 row_mask:0xf bank_mask:0xf
	v_mul_f32_dpp v143, v143, v143 row_shr:8 row_mask:0xf bank_mask:0xf
	v_mul_f32_dpp v144, v144, v144 row_shr:8 row_mask:0xf bank_mask:0xf
	v_mul_f32_dpp v145, v145, v145 row_shr:8 row_mask:0xf bank_mask:0xf
	v_mul_f32_dpp v146, v146, v146 row_shr:8 row_mask:0xf bank_mask:0xf
	v_mul_f32_dpp v147, v147, v147 row_shr:8 row_mask:0xf bank_mask:0xf
	v_mul_f32_dpp v148, v148, v148 row_shr:8 row_mask:0xf bank_mask:0xf
	v_mul_f32_dpp v149, v149, v149 row_shr:8 row_mask:0xf bank_mask:0xf
	v_mul_f32_dpp v150, v150, v150 row_shr:8 row_mask:0xf bank_mask:0xf
	v_mul_f32_dpp v151, v151, v151 row_shr:8 row_mask:0xf bank_mask:0xf
	v_mul_f32_dpp v152, v152, v152 row_shr:8 row_mask:0xf bank_mask:0xf
	v_mul_f32_dpp v153, v153, v153 row_shr:8 row_mask:0xf bank_mask:0xf
	v_mul_f32_dpp v154, v154, v154 row_shr:8 row_mask:0xf bank_mask:0xf
	v_mul_f32_dpp v155, v155, v155 row_shr:8 row_mask:0xf bank_mask:0xf
	v_mul_f32_dpp v156, v156, v156 row_shr:8 row_mask:0xf bank_mask:0xf
	s_add_u32 m0, s71, 6144
	s_nop 0
	global_load_lds_dwordx4 v231, s[30:31]
	v_mul_f32_dpp v157, v157, v157 row_shr:8 row_mask:0xf bank_mask:0xf
	v_mul_f32_dpp v158, v158, v158 row_shr:8 row_mask:0xf bank_mask:0xf
	v_mul_f32_dpp v159, v159, v159 row_shr:8 row_mask:0xf bank_mask:0xf
	v_mul_f32_dpp v128, v128, v128 row_bcast:15 row_mask:0xa bank_mask:0xf
	v_mul_f32_dpp v129, v129, v129 row_bcast:15 row_mask:0xa bank_mask:0xf
	v_mul_f32_dpp v130, v130, v130 row_bcast:15 row_mask:0xa bank_mask:0xf
	v_mul_f32_dpp v131, v131, v131 row_bcast:15 row_mask:0xa bank_mask:0xf
	v_mul_f32_dpp v132, v132, v132 row_bcast:15 row_mask:0xa bank_mask:0xf
	v_mul_f32_dpp v133, v133, v133 row_bcast:15 row_mask:0xa bank_mask:0xf
	v_mul_f32_dpp v134, v134, v134 row_bcast:15 row_mask:0xa bank_mask:0xf
	v_mul_f32_dpp v135, v135, v135 row_bcast:15 row_mask:0xa bank_mask:0xf
	v_mul_f32_dpp v136, v136, v136 row_bcast:15 row_mask:0xa bank_mask:0xf
	v_mul_f32_dpp v137, v137, v137 row_bcast:15 row_mask:0xa bank_mask:0xf
	v_mul_f32_dpp v138, v138, v138 row_bcast:15 row_mask:0xa bank_mask:0xf
	v_mul_f32_dpp v139, v139, v139 row_bcast:15 row_mask:0xa bank_mask:0xf
	v_mul_f32_dpp v140, v140, v140 row_bcast:15 row_mask:0xa bank_mask:0xf
	v_mul_f32_dpp v141, v141, v141 row_bcast:15 row_mask:0xa bank_mask:0xf
	v_mul_f32_dpp v142, v142, v142 row_bcast:15 row_mask:0xa bank_mask:0xf
	v_mul_f32_dpp v143, v143, v143 row_bcast:15 row_mask:0xa bank_mask:0xf
	v_mul_f32_dpp v144, v144, v144 row_bcast:15 row_mask:0xa bank_mask:0xf
	v_mul_f32_dpp v145, v145, v145 row_bcast:15 row_mask:0xa bank_mask:0xf
	s_add_u32 m0, s71, 3072
	s_nop 0
	global_load_lds_dwordx4 v232, s[14:15]
	v_mul_f32_dpp v146, v146, v146 row_bcast:15 row_mask:0xa bank_mask:0xf
	v_mul_f32_dpp v147, v147, v147 row_bcast:15 row_mask:0xa bank_mask:0xf
	v_mul_f32_dpp v148, v148, v148 row_bcast:15 row_mask:0xa bank_mask:0xf
	v_mul_f32_dpp v149, v149, v149 row_bcast:15 row_mask:0xa bank_mask:0xf
	v_mul_f32_dpp v150, v150, v150 row_bcast:15 row_mask:0xa bank_mask:0xf
	v_mul_f32_dpp v151, v151, v151 row_bcast:15 row_mask:0xa bank_mask:0xf
	v_mul_f32_dpp v152, v152, v152 row_bcast:15 row_mask:0xa bank_mask:0xf
	v_mul_f32_dpp v153, v153, v153 row_bcast:15 row_mask:0xa bank_mask:0xf
	v_mul_f32_dpp v154, v154, v154 row_bcast:15 row_mask:0xa bank_mask:0xf
	v_mul_f32_dpp v155, v155, v155 row_bcast:15 row_mask:0xa bank_mask:0xf
	v_mul_f32_dpp v156, v156, v156 row_bcast:15 row_mask:0xa bank_mask:0xf
	v_mul_f32_dpp v157, v157, v157 row_bcast:15 row_mask:0xa bank_mask:0xf
	v_mul_f32_dpp v158, v158, v158 row_bcast:15 row_mask:0xa bank_mask:0xf
	v_mul_f32_dpp v159, v159, v159 row_bcast:15 row_mask:0xa bank_mask:0xf
	v_mul_f32_dpp v128, v128, v128 row_bcast:31 row_mask:0xc bank_mask:0xf
	v_mul_f32_dpp v129, v129, v129 row_bcast:31 row_mask:0xc bank_mask:0xf
	v_mul_f32_dpp v130, v130, v130 row_bcast:31 row_mask:0xc bank_mask:0xf
	v_mul_f32_dpp v131, v131, v131 row_bcast:31 row_mask:0xc bank_mask:0xf
	v_mul_f32_dpp v132, v132, v132 row_bcast:31 row_mask:0xc bank_mask:0xf
	v_mul_f32_dpp v133, v133, v133 row_bcast:31 row_mask:0xc bank_mask:0xf
	v_mul_f32_dpp v134, v134, v134 row_bcast:31 row_mask:0xc bank_mask:0xf
	s_add_u32 m0, s71, 7168
	s_nop 0
	global_load_lds_dwordx4 v232, s[30:31]
	v_add_u32_e32 v228, s76, v228
	v_add_u32_e32 v230, s76, v230
	v_add_u32_e32 v231, s76, v231
	v_add_u32_e32 v232, s76, v232
	v_mul_f32_dpp v135, v135, v135 row_bcast:31 row_mask:0xc bank_mask:0xf
	v_mul_f32_dpp v136, v136, v136 row_bcast:31 row_mask:0xc bank_mask:0xf
	v_mul_f32_dpp v137, v137, v137 row_bcast:31 row_mask:0xc bank_mask:0xf
	v_mul_f32_dpp v138, v138, v138 row_bcast:31 row_mask:0xc bank_mask:0xf
	v_mul_f32_dpp v139, v139, v139 row_bcast:31 row_mask:0xc bank_mask:0xf
	v_mul_f32_dpp v140, v140, v140 row_bcast:31 row_mask:0xc bank_mask:0xf
	v_mul_f32_dpp v141, v141, v141 row_bcast:31 row_mask:0xc bank_mask:0xf
	v_mul_f32_dpp v142, v142, v142 row_bcast:31 row_mask:0xc bank_mask:0xf
	v_mul_f32_dpp v143, v143, v143 row_bcast:31 row_mask:0xc bank_mask:0xf
	v_mul_f32_dpp v144, v144, v144 row_bcast:31 row_mask:0xc bank_mask:0xf
	v_mul_f32_dpp v145, v145, v145 row_bcast:31 row_mask:0xc bank_mask:0xf
	v_mul_f32_dpp v146, v146, v146 row_bcast:31 row_mask:0xc bank_mask:0xf
	v_mul_f32_dpp v147, v147, v147 row_bcast:31 row_mask:0xc bank_mask:0xf
	v_mul_f32_dpp v148, v148, v148 row_bcast:31 row_mask:0xc bank_mask:0xf
	v_mul_f32_dpp v149, v149, v149 row_bcast:31 row_mask:0xc bank_mask:0xf
	v_mul_f32_dpp v150, v150, v150 row_bcast:31 row_mask:0xc bank_mask:0xf
	v_mul_f32_dpp v151, v151, v151 row_bcast:31 row_mask:0xc bank_mask:0xf
	v_mul_f32_dpp v152, v152, v152 row_bcast:31 row_mask:0xc bank_mask:0xf
	v_mul_f32_dpp v153, v153, v153 row_bcast:31 row_mask:0xc bank_mask:0xf
	v_mul_f32_dpp v154, v154, v154 row_bcast:31 row_mask:0xc bank_mask:0xf
	v_mul_f32_dpp v155, v155, v155 row_bcast:31 row_mask:0xc bank_mask:0xf
	v_mul_f32_dpp v156, v156, v156 row_bcast:31 row_mask:0xc bank_mask:0xf
	v_mul_f32_dpp v157, v157, v157 row_bcast:31 row_mask:0xc bank_mask:0xf
	v_mul_f32_dpp v158, v158, v158 row_bcast:31 row_mask:0xc bank_mask:0xf
	v_mul_f32_dpp v159, v159, v159 row_bcast:31 row_mask:0xc bank_mask:0xf
	s_mov_b32 exec_lo, 0
	s_brev_b32 exec_hi, 1
	ds_write_b128 v247, v[128:131] offset:512
	ds_write_b128 v247, v[132:135] offset:528
	ds_write_b128 v247, v[136:139] offset:544
	ds_write_b128 v247, v[140:143] offset:560
	ds_write_b128 v247, v[144:147] offset:576
	ds_write_b128 v247, v[148:151] offset:592
	ds_write_b128 v247, v[152:155] offset:608
	ds_write_b128 v247, v[156:159] offset:624
	s_mov_b64 exec, -1
	v_rcp_f32_e32 v220, v128
	v_rcp_f32_e32 v221, v129
	v_lshlrev_b32_e32 v218, 16, v0
	v_and_b32_e32 v219, 0xffff0000, v0
	v_pk_mul_f32 v[218:219], v[128:129], v[218:219]
	v_pk_mul_f32 v[220:221], v[220:221], v[96:97]
	v_cvt_pk_bf16_f32 v202, v218, v219
	v_cvt_pk_bf16_f32 v184, v220, v221
	v_rcp_f32_e32 v220, v130
	v_rcp_f32_e32 v221, v131
	v_lshlrev_b32_e32 v218, 16, v1
	v_and_b32_e32 v219, 0xffff0000, v1
	v_pk_mul_f32 v[218:219], v[130:131], v[218:219]
	v_pk_mul_f32 v[220:221], v[220:221], v[98:99]
	v_cvt_pk_bf16_f32 v203, v218, v219
	v_cvt_pk_bf16_f32 v185, v220, v221
	v_rcp_f32_e32 v220, v132
	v_rcp_f32_e32 v221, v133
	v_lshlrev_b32_e32 v218, 16, v2
	v_and_b32_e32 v219, 0xffff0000, v2
	v_pk_mul_f32 v[218:219], v[132:133], v[218:219]
	v_pk_mul_f32 v[220:221], v[220:221], v[100:101]
	v_cvt_pk_bf16_f32 v204, v218, v219
	v_cvt_pk_bf16_f32 v186, v220, v221
	v_rcp_f32_e32 v220, v134
	v_rcp_f32_e32 v221, v135
	v_lshlrev_b32_e32 v218, 16, v3
	v_and_b32_e32 v219, 0xffff0000, v3
	v_pk_mul_f32 v[218:219], v[134:135], v[218:219]
	v_pk_mul_f32 v[220:221], v[220:221], v[102:103]
	v_cvt_pk_bf16_f32 v205, v218, v219
	v_cvt_pk_bf16_f32 v187, v220, v221
	v_rcp_f32_e32 v220, v136
	v_rcp_f32_e32 v221, v137
	v_lshlrev_b32_e32 v218, 16, v4
	v_and_b32_e32 v219, 0xffff0000, v4
	v_pk_mul_f32 v[218:219], v[136:137], v[218:219]
	v_pk_mul_f32 v[220:221], v[220:221], v[104:105]
	v_cvt_pk_bf16_f32 v206, v218, v219
	v_cvt_pk_bf16_f32 v188, v220, v221
	v_rcp_f32_e32 v220, v138
	v_rcp_f32_e32 v221, v139
	v_lshlrev_b32_e32 v218, 16, v5
	v_and_b32_e32 v219, 0xffff0000, v5
	v_pk_mul_f32 v[218:219], v[138:139], v[218:219]
	v_pk_mul_f32 v[220:221], v[220:221], v[106:107]
	v_cvt_pk_bf16_f32 v207, v218, v219
	v_cvt_pk_bf16_f32 v189, v220, v221
	v_rcp_f32_e32 v220, v140
	v_rcp_f32_e32 v221, v141
	v_lshlrev_b32_e32 v218, 16, v6
	v_and_b32_e32 v219, 0xffff0000, v6
	v_pk_mul_f32 v[218:219], v[140:141], v[218:219]
	v_pk_mul_f32 v[220:221], v[220:221], v[108:109]
	v_cvt_pk_bf16_f32 v208, v218, v219
	v_cvt_pk_bf16_f32 v190, v220, v221
	v_rcp_f32_e32 v220, v142
	v_rcp_f32_e32 v221, v143
	v_lshlrev_b32_e32 v218, 16, v7
	v_and_b32_e32 v219, 0xffff0000, v7
	v_pk_mul_f32 v[218:219], v[142:143], v[218:219]
	v_pk_mul_f32 v[220:221], v[220:221], v[110:111]
	v_cvt_pk_bf16_f32 v209, v218, v219
	v_cvt_pk_bf16_f32 v191, v220, v221
	v_rcp_f32_e32 v220, v144
	v_rcp_f32_e32 v221, v145
	v_lshlrev_b32_e32 v218, 16, v8
	v_and_b32_e32 v219, 0xffff0000, v8
	v_pk_mul_f32 v[218:219], v[144:145], v[218:219]
	v_pk_mul_f32 v[220:221], v[220:221], v[112:113]
	v_cvt_pk_bf16_f32 v210, v218, v219
	v_cvt_pk_bf16_f32 v192, v220, v221
	v_rcp_f32_e32 v220, v146
	v_rcp_f32_e32 v221, v147
	v_lshlrev_b32_e32 v218, 16, v9
	v_and_b32_e32 v219, 0xffff0000, v9
	v_pk_mul_f32 v[218:219], v[146:147], v[218:219]
	v_pk_mul_f32 v[220:221], v[220:221], v[114:115]
	v_cvt_pk_bf16_f32 v211, v218, v219
	v_cvt_pk_bf16_f32 v193, v220, v221
	v_rcp_f32_e32 v220, v148
	v_rcp_f32_e32 v221, v149
	v_lshlrev_b32_e32 v218, 16, v10
	v_and_b32_e32 v219, 0xffff0000, v10
	v_pk_mul_f32 v[218:219], v[148:149], v[218:219]
	v_pk_mul_f32 v[220:221], v[220:221], v[116:117]
	v_cvt_pk_bf16_f32 v212, v218, v219
	v_cvt_pk_bf16_f32 v194, v220, v221
	v_rcp_f32_e32 v220, v150
	v_rcp_f32_e32 v221, v151
	v_lshlrev_b32_e32 v218, 16, v11
	v_and_b32_e32 v219, 0xffff0000, v11
	v_pk_mul_f32 v[218:219], v[150:151], v[218:219]
	v_pk_mul_f32 v[220:221], v[220:221], v[118:119]
	v_cvt_pk_bf16_f32 v213, v218, v219
	v_cvt_pk_bf16_f32 v195, v220, v221
	v_rcp_f32_e32 v220, v152
	v_rcp_f32_e32 v221, v153
	v_lshlrev_b32_e32 v218, 16, v12
	v_and_b32_e32 v219, 0xffff0000, v12
	v_pk_mul_f32 v[218:219], v[152:153], v[218:219]
	v_pk_mul_f32 v[220:221], v[220:221], v[120:121]
	v_cvt_pk_bf16_f32 v214, v218, v219
	v_cvt_pk_bf16_f32 v196, v220, v221
	v_rcp_f32_e32 v220, v154
	v_rcp_f32_e32 v221, v155
	v_lshlrev_b32_e32 v218, 16, v13
	v_and_b32_e32 v219, 0xffff0000, v13
	v_pk_mul_f32 v[218:219], v[154:155], v[218:219]
	v_pk_mul_f32 v[220:221], v[220:221], v[122:123]
	v_cvt_pk_bf16_f32 v215, v218, v219
	v_cvt_pk_bf16_f32 v197, v220, v221
	v_rcp_f32_e32 v220, v156
	v_rcp_f32_e32 v221, v157
	v_lshlrev_b32_e32 v218, 16, v14
	v_and_b32_e32 v219, 0xffff0000, v14
	v_pk_mul_f32 v[218:219], v[156:157], v[218:219]
	v_pk_mul_f32 v[220:221], v[220:221], v[124:125]
	v_cvt_pk_bf16_f32 v216, v218, v219
	v_cvt_pk_bf16_f32 v198, v220, v221
	v_rcp_f32_e32 v220, v158
	v_rcp_f32_e32 v221, v159
	v_lshlrev_b32_e32 v218, 16, v15
	v_and_b32_e32 v219, 0xffff0000, v15
	v_pk_mul_f32 v[218:219], v[158:159], v[218:219]
	v_pk_mul_f32 v[220:221], v[220:221], v[126:127]
	v_cvt_pk_bf16_f32 v217, v218, v219
	v_cvt_pk_bf16_f32 v199, v220, v221
	ds_write_b128 v222, v[184:187] offset:17408
	ds_write_b128 v223, v[188:191] offset:17408
	ds_write_b128 v224, v[192:195] offset:17408
	ds_write_b128 v225, v[196:199] offset:17408
	ds_write_b128 v227, v[202:205]
	ds_write_b128 v227, v[206:209] offset:16
	ds_write_b128 v227, v[210:213] offset:32
	ds_write_b128 v227, v[214:217] offset:48
	s_waitcnt vmcnt(8)
	s_waitcnt lgkmcnt(0)
	s_barrier
	s_add_u32 s70, s70, 1
	s_cmp_lt_u32 s70, 32
	s_cbranch_scc1 .Lh2_prep_loop
	s_waitcnt vmcnt(0)
	s_barrier
	s_branch .Lh2_done

.Lh2_done:
	s_barrier
	s_branch .LBB0_445
	s_nop 0
	s_nop 0
	s_nop 0
	s_nop 0
	s_nop 0
	s_nop 0
	s_nop 0
	s_nop 0
	s_nop 0
	s_nop 0
	s_nop 0
	s_nop 0
	s_nop 0
	s_nop 0
	s_nop 0
	s_nop 0
	s_nop 0
	s_nop 0
	s_nop 0
	s_nop 0
	s_nop 0
	s_nop 0
	s_nop 0
	s_nop 0
	s_nop 0
	s_nop 0
	s_nop 0
	s_nop 0
	s_nop 0
	s_nop 0
	s_nop 0
